# combine CAT stores write-through (sc1) so the scan publish L2 writeback is cheaper
# speedup vs baseline: 1.0070x; 1.0044x over previous
; __device__ __forceinline__ unsigned pk2(float lo, float hi) { f32x2_t v = {lo, hi}; bf16x2_t b = __builtin_convertvector(v, bf16x2_t); return __builtin_bit_cast(unsigned, b); }
; __device__ __forceinline__ float bflo(unsigned w) { return __uint_as_float(w << 16); }
; __device__ __forceinline__ float bfhi(unsigned w) { return __uint_as_float(w & 0xffff0000u); }
; __device__ __forceinline__ bf16* po_base(unsigned char* ws, int pat) { return (bf16*)(ws + (pat < 2 ? 436 * MiB + (size_t)pat * 32 * MiB : WS_Y)); }
; __device__ __forceinline__ void attn_combine(unsigned char* ws, const float* __restrict__ PM, bf16* CAT, int gtid, int gthreads, int iend = S * 128) {
;     for (int idx = gtid; idx < iend; idx += gthreads) {
;         const int t = idx >> 7, c = (idx & 127) * 8, hh = c >> 7;
;         float mm[3], ll[3];
; #pragma unroll
;         for (int p = 0; p < 3; ++p) { const f32x2_t ml = *(const f32x2_t*)(PM + (((size_t)p * S + t) * 8 + hh) * 2); mm[p] = ml[0]; ll[p] = ml[1]; }
;         const float ma = fmaxf(mm[0], fmaxf(mm[1], mm[2]));
;         float w[3], den = 0.f;
; #pragma unroll
;         for (int p = 0; p < 3; ++p) { w[p] = exp2f(mm[p] - ma) * ll[p]; den += w[p]; }
;         const float inv = 1.f / den;
;         float o[8] = {0.f, 0.f, 0.f, 0.f, 0.f, 0.f, 0.f, 0.f};
; #pragma unroll
;         for (int p = 0; p < 3; ++p) {
;             const u32x4 v = *(const u32x4*)(po_base(ws, p) + (size_t)t * 1024 + c); const float wp = w[p] * inv;
;             o[0] += wp * bflo(v.x); o[1] += wp * bfhi(v.x); o[2] += wp * bflo(v.y); o[3] += wp * bfhi(v.y); o[4] += wp * bflo(v.z); o[5] += wp * bfhi(v.z); o[6] += wp * bflo(v.w); o[7] += wp * bfhi(v.w);
;         }
;         u32x4 ov; ov.x = pk2(o[0], o[1]); ov.y = pk2(o[2], o[3]); ov.z = pk2(o[4], o[5]); ov.w = pk2(o[6], o[7]);
;         *(u32x4*)(CAT + (size_t)t * 2048 + c) = ov;
.Lcmb_loop:
	v_min_i32_e32 v60, s1, v2
	v_ashrrev_i32_e32 v59, 7, v60
	v_lshrrev_b32_e32 v61, 1, v60
	v_and_b32_e32 v61, 56, v61
	v_lshl_or_b32 v61, v59, 6, v61
	global_load_dwordx2 v[40:41], v61, s[26:27]
	global_load_dwordx2 v[42:43], v61, s[6:7]
	global_load_dwordx2 v[44:45], v61, s[8:9]
	v_and_b32_e32 v58, 0x7f, v60
	v_lshlrev_b32_e32 v60, 4, v60
	v_lshlrev_b32_e32 v58, 4, v58
	global_load_dwordx4 v[46:49], v60, s[16:17]
	v_lshl_or_b32 v58, v59, 12, v58
	global_load_dwordx4 v[50:53], v60, s[20:21]
	global_load_dwordx4 v[54:57], v60, s[22:23]
	v_add_u32_e32 v84, 512, v2
	v_min_i32_e32 v84, s1, v84
	v_ashrrev_i32_e32 v83, 7, v84
	v_lshrrev_b32_e32 v85, 1, v84
	v_and_b32_e32 v85, 56, v85
	v_lshl_or_b32 v85, v83, 6, v85
	global_load_dwordx2 v[64:65], v85, s[26:27]
	global_load_dwordx2 v[66:67], v85, s[6:7]
	global_load_dwordx2 v[68:69], v85, s[8:9]
	v_and_b32_e32 v82, 0x7f, v84
	v_lshlrev_b32_e32 v84, 4, v84
	v_lshlrev_b32_e32 v82, 4, v82
	global_load_dwordx4 v[70:73], v84, s[16:17]
	v_lshl_or_b32 v82, v83, 12, v82
	global_load_dwordx4 v[74:77], v84, s[20:21]
	global_load_dwordx4 v[78:81], v84, s[22:23]
	v_add_u32_e32 v108, 1024, v2
	v_min_i32_e32 v108, s1, v108
	v_ashrrev_i32_e32 v107, 7, v108
	v_lshrrev_b32_e32 v109, 1, v108
	v_and_b32_e32 v109, 56, v109
	v_lshl_or_b32 v109, v107, 6, v109
	global_load_dwordx2 v[88:89], v109, s[26:27]
	global_load_dwordx2 v[90:91], v109, s[6:7]
	global_load_dwordx2 v[92:93], v109, s[8:9]
	v_and_b32_e32 v106, 0x7f, v108
	v_lshlrev_b32_e32 v108, 4, v108
	v_lshlrev_b32_e32 v106, 4, v106
	global_load_dwordx4 v[94:97], v108, s[16:17]
	v_lshl_or_b32 v106, v107, 12, v106
	global_load_dwordx4 v[98:101], v108, s[20:21]
	global_load_dwordx4 v[102:105], v108, s[22:23]
	v_add_u32_e32 v132, 1536, v2
	v_min_i32_e32 v132, s1, v132
	v_ashrrev_i32_e32 v131, 7, v132
	v_lshrrev_b32_e32 v133, 1, v132
	v_and_b32_e32 v133, 56, v133
	v_lshl_or_b32 v133, v131, 6, v133
	global_load_dwordx2 v[112:113], v133, s[26:27]
	global_load_dwordx2 v[114:115], v133, s[6:7]
	global_load_dwordx2 v[116:117], v133, s[8:9]
	v_and_b32_e32 v130, 0x7f, v132
	v_lshlrev_b32_e32 v132, 4, v132
	v_lshlrev_b32_e32 v130, 4, v130
	global_load_dwordx4 v[118:121], v132, s[16:17]
	v_lshl_or_b32 v130, v131, 12, v130
	global_load_dwordx4 v[122:125], v132, s[20:21]
	global_load_dwordx4 v[126:129], v132, s[22:23]
	v_add_u32_e32 v2, 2048, v2
	s_add_i32 s0, s0, -1
	s_waitcnt vmcnt(18)
	v_max3_f32 v0, v40, v42, v44
	v_sub_f32_e32 v18, v40, v0
	v_sub_f32_e32 v36, v42, v0
	v_sub_f32_e32 v0, v44, v0
	v_cmp_gt_f32_e32 vcc, s19, v18
	v_cmp_gt_f32_e64 s[4:5], s19, v36
	v_cmp_gt_f32_e64 s[32:33], s19, v0
	v_cndmask_b32_e32 v37, 0, v4, vcc
	v_cndmask_b32_e64 v38, 0, v4, s[4:5]
	v_cndmask_b32_e64 v39, 0, v4, s[32:33]
	v_add_f32_e32 v18, v18, v37
	v_add_f32_e32 v36, v36, v38
	v_add_f32_e32 v0, v0, v39
	v_exp_f32_e32 v18, v18
	v_exp_f32_e32 v36, v36
	v_exp_f32_e32 v0, v0
	v_cndmask_b32_e32 v37, 0, v5, vcc
	v_cndmask_b32_e64 v38, 0, v5, s[4:5]
	v_cndmask_b32_e64 v39, 0, v5, s[32:33]
	v_mov_b32_e32 v20, v45
	v_mov_b32_e32 v21, v43
	v_ldexp_f32 v18, v18, v37
	v_ldexp_f32 v37, v36, v38
	v_ldexp_f32 v36, v0, v39
	v_mul_f32_e32 v0, v41, v18
	v_fma_f32 v38, v41, v18, 0
	v_pk_mul_f32 v[18:19], v[20:21], v[36:37]
	v_add_f32_e32 v20, v19, v38
	v_add_f32_e32 v20, v18, v20
	v_div_scale_f32 v21, s[4:5], v20, v20, 1.0
	v_rcp_f32_e32 v37, v21
	v_div_scale_f32 v36, vcc, 1.0, v20, 1.0
	v_fma_f32 v38, -v21, v37, 1.0
	v_fmac_f32_e32 v37, v38, v37
	v_mul_f32_e32 v38, v36, v37
	v_fma_f32 v39, -v21, v38, v36
	v_fmac_f32_e32 v38, v39, v37
	v_fma_f32 v21, -v21, v38, v36
	v_div_fmas_f32 v21, v21, v37, v38
	v_div_fixup_f32 v21, v21, v20, 1.0
	v_mul_f32_e32 v0, v0, v21
	v_mul_f32_e32 v20, v19, v21
	v_mul_f32_e32 v18, v18, v21
	v_lshlrev_b32_e32 v22, 16, v46
	v_and_b32_e32 v23, 0xffff0000, v46
	v_lshlrev_b32_e32 v6, 16, v47
	v_and_b32_e32 v7, 0xffff0000, v47
	v_lshlrev_b32_e32 v30, 16, v48
	v_and_b32_e32 v31, 0xffff0000, v48
	v_lshlrev_b32_e32 v8, 16, v49
	v_and_b32_e32 v9, 0xffff0000, v49
	v_lshlrev_b32_e32 v26, 16, v50
	v_and_b32_e32 v27, 0xffff0000, v50
	v_lshlrev_b32_e32 v10, 16, v51
	v_and_b32_e32 v11, 0xffff0000, v51
	v_lshlrev_b32_e32 v32, 16, v52
	v_and_b32_e32 v33, 0xffff0000, v52
	v_lshlrev_b32_e32 v12, 16, v53
	v_and_b32_e32 v13, 0xffff0000, v53
	v_pk_fma_f32 v[22:23], v[0:1], v[22:23], 0 op_sel_hi:[0,1,0]
	v_pk_fma_f32 v[6:7], v[0:1], v[6:7], 0 op_sel_hi:[0,1,0]
	v_pk_fma_f32 v[30:31], v[0:1], v[30:31], 0 op_sel_hi:[0,1,0]
	v_pk_fma_f32 v[8:9], v[0:1], v[8:9], 0 op_sel_hi:[0,1,0]
	v_lshlrev_b32_e32 v28, 16, v54
	v_and_b32_e32 v29, 0xffff0000, v54
	v_lshlrev_b32_e32 v14, 16, v55
	v_and_b32_e32 v15, 0xffff0000, v55
	v_lshlrev_b32_e32 v34, 16, v56
	v_and_b32_e32 v35, 0xffff0000, v56
	v_lshlrev_b32_e32 v16, 16, v57
	v_and_b32_e32 v17, 0xffff0000, v57
	v_pk_fma_f32 v[22:23], v[20:21], v[26:27], v[22:23] op_sel_hi:[0,1,1]
	v_pk_fma_f32 v[6:7], v[20:21], v[10:11], v[6:7] op_sel_hi:[0,1,1]
	v_pk_fma_f32 v[10:11], v[20:21], v[32:33], v[30:31] op_sel_hi:[0,1,1]
	v_pk_fma_f32 v[8:9], v[20:21], v[12:13], v[8:9] op_sel_hi:[0,1,1]
	v_pk_fma_f32 v[12:13], v[18:19], v[28:29], v[22:23] op_sel_hi:[0,1,1]
	v_pk_fma_f32 v[14:15], v[18:19], v[14:15], v[6:7] op_sel_hi:[0,1,1]
	v_pk_fma_f32 v[10:11], v[18:19], v[34:35], v[10:11] op_sel_hi:[0,1,1]
	v_pk_fma_f32 v[16:17], v[18:19], v[16:17], v[8:9] op_sel_hi:[0,1,1]
	v_cvt_pk_bf16_f32 v46, v12, v13
	v_cvt_pk_bf16_f32 v47, v14, v15
	v_cvt_pk_bf16_f32 v48, v10, v11
	v_cvt_pk_bf16_f32 v49, v16, v17
	global_store_dwordx4 v58, v[46:49], s[10:11] sc1
	s_waitcnt vmcnt(13)
; __device__ __forceinline__ unsigned pk2(float lo, float hi) { f32x2_t v = {lo, hi}; bf16x2_t b = __builtin_convertvector(v, bf16x2_t); return __builtin_bit_cast(unsigned, b); }
; __device__ __forceinline__ float bflo(unsigned w) { return __uint_as_float(w << 16); }
; __device__ __forceinline__ float bfhi(unsigned w) { return __uint_as_float(w & 0xffff0000u); }
; __device__ __forceinline__ bf16* po_base(unsigned char* ws, int pat) { return (bf16*)(ws + (pat < 2 ? 436 * MiB + (size_t)pat * 32 * MiB : WS_Y)); }
; __device__ __forceinline__ void attn_combine(unsigned char* ws, const float* __restrict__ PM, bf16* CAT, int gtid, int gthreads, int iend = S * 128) {
;     for (int idx = gtid; idx < iend; idx += gthreads) {
;         const int t = idx >> 7, c = (idx & 127) * 8, hh = c >> 7;
;         float mm[3], ll[3];
; #pragma unroll
;         for (int p = 0; p < 3; ++p) { const f32x2_t ml = *(const f32x2_t*)(PM + (((size_t)p * S + t) * 8 + hh) * 2); mm[p] = ml[0]; ll[p] = ml[1]; }
;         const float ma = fmaxf(mm[0], fmaxf(mm[1], mm[2]));
;         float w[3], den = 0.f;
; #pragma unroll
;         for (int p = 0; p < 3; ++p) { w[p] = exp2f(mm[p] - ma) * ll[p]; den += w[p]; }
;         const float inv = 1.f / den;
;         float o[8] = {0.f, 0.f, 0.f, 0.f, 0.f, 0.f, 0.f, 0.f};
; #pragma unroll
;         for (int p = 0; p < 3; ++p) {
;             const u32x4 v = *(const u32x4*)(po_base(ws, p) + (size_t)t * 1024 + c); const float wp = w[p] * inv;
;             o[0] += wp * bflo(v.x); o[1] += wp * bfhi(v.x); o[2] += wp * bflo(v.y); o[3] += wp * bfhi(v.y); o[4] += wp * bflo(v.z); o[5] += wp * bfhi(v.z); o[6] += wp * bflo(v.w); o[7] += wp * bfhi(v.w);
;         }
;         u32x4 ov; ov.x = pk2(o[0], o[1]); ov.y = pk2(o[2], o[3]); ov.z = pk2(o[4], o[5]); ov.w = pk2(o[6], o[7]);
;         *(u32x4*)(CAT + (size_t)t * 2048 + c) = ov;
	v_max3_f32 v0, v64, v66, v68
	v_sub_f32_e32 v18, v64, v0
	v_sub_f32_e32 v36, v66, v0
	v_sub_f32_e32 v0, v68, v0
	v_cmp_gt_f32_e32 vcc, s19, v18
	v_cmp_gt_f32_e64 s[4:5], s19, v36
	v_cmp_gt_f32_e64 s[32:33], s19, v0
	v_cndmask_b32_e32 v37, 0, v4, vcc
	v_cndmask_b32_e64 v38, 0, v4, s[4:5]
	v_cndmask_b32_e64 v39, 0, v4, s[32:33]
	v_add_f32_e32 v18, v18, v37
	v_add_f32_e32 v36, v36, v38
	v_add_f32_e32 v0, v0, v39
	v_exp_f32_e32 v18, v18
	v_exp_f32_e32 v36, v36
	v_exp_f32_e32 v0, v0
	v_cndmask_b32_e32 v37, 0, v5, vcc
	v_cndmask_b32_e64 v38, 0, v5, s[4:5]
	v_cndmask_b32_e64 v39, 0, v5, s[32:33]
	v_mov_b32_e32 v20, v69
	v_mov_b32_e32 v21, v67
	v_ldexp_f32 v18, v18, v37
	v_ldexp_f32 v37, v36, v38
	v_ldexp_f32 v36, v0, v39
	v_mul_f32_e32 v0, v65, v18
	v_fma_f32 v38, v65, v18, 0
	v_pk_mul_f32 v[18:19], v[20:21], v[36:37]
	v_add_f32_e32 v20, v19, v38
	v_add_f32_e32 v20, v18, v20
	v_div_scale_f32 v21, s[4:5], v20, v20, 1.0
	v_rcp_f32_e32 v37, v21
	v_div_scale_f32 v36, vcc, 1.0, v20, 1.0
	v_fma_f32 v38, -v21, v37, 1.0
	v_fmac_f32_e32 v37, v38, v37
	v_mul_f32_e32 v38, v36, v37
	v_fma_f32 v39, -v21, v38, v36
	v_fmac_f32_e32 v38, v39, v37
	v_fma_f32 v21, -v21, v38, v36
	v_div_fmas_f32 v21, v21, v37, v38
	v_div_fixup_f32 v21, v21, v20, 1.0
	v_mul_f32_e32 v0, v0, v21
	v_mul_f32_e32 v20, v19, v21
	v_mul_f32_e32 v18, v18, v21
	v_lshlrev_b32_e32 v22, 16, v70
	v_and_b32_e32 v23, 0xffff0000, v70
	v_lshlrev_b32_e32 v6, 16, v71
	v_and_b32_e32 v7, 0xffff0000, v71
	v_lshlrev_b32_e32 v30, 16, v72
	v_and_b32_e32 v31, 0xffff0000, v72
	v_lshlrev_b32_e32 v8, 16, v73
	v_and_b32_e32 v9, 0xffff0000, v73
	v_lshlrev_b32_e32 v26, 16, v74
	v_and_b32_e32 v27, 0xffff0000, v74
	v_lshlrev_b32_e32 v10, 16, v75
	v_and_b32_e32 v11, 0xffff0000, v75
	v_lshlrev_b32_e32 v32, 16, v76
	v_and_b32_e32 v33, 0xffff0000, v76
	v_lshlrev_b32_e32 v12, 16, v77
	v_and_b32_e32 v13, 0xffff0000, v77
	v_pk_fma_f32 v[22:23], v[0:1], v[22:23], 0 op_sel_hi:[0,1,0]
	v_pk_fma_f32 v[6:7], v[0:1], v[6:7], 0 op_sel_hi:[0,1,0]
	v_pk_fma_f32 v[30:31], v[0:1], v[30:31], 0 op_sel_hi:[0,1,0]
	v_pk_fma_f32 v[8:9], v[0:1], v[8:9], 0 op_sel_hi:[0,1,0]
	v_lshlrev_b32_e32 v28, 16, v78
	v_and_b32_e32 v29, 0xffff0000, v78
	v_lshlrev_b32_e32 v14, 16, v79
	v_and_b32_e32 v15, 0xffff0000, v79
	v_lshlrev_b32_e32 v34, 16, v80
	v_and_b32_e32 v35, 0xffff0000, v80
	v_lshlrev_b32_e32 v16, 16, v81
	v_and_b32_e32 v17, 0xffff0000, v81
	v_pk_fma_f32 v[22:23], v[20:21], v[26:27], v[22:23] op_sel_hi:[0,1,1]
	v_pk_fma_f32 v[6:7], v[20:21], v[10:11], v[6:7] op_sel_hi:[0,1,1]
	v_pk_fma_f32 v[10:11], v[20:21], v[32:33], v[30:31] op_sel_hi:[0,1,1]
	v_pk_fma_f32 v[8:9], v[20:21], v[12:13], v[8:9] op_sel_hi:[0,1,1]
	v_pk_fma_f32 v[12:13], v[18:19], v[28:29], v[22:23] op_sel_hi:[0,1,1]
	v_pk_fma_f32 v[14:15], v[18:19], v[14:15], v[6:7] op_sel_hi:[0,1,1]
	v_pk_fma_f32 v[10:11], v[18:19], v[34:35], v[10:11] op_sel_hi:[0,1,1]
	v_pk_fma_f32 v[16:17], v[18:19], v[16:17], v[8:9] op_sel_hi:[0,1,1]
	v_cvt_pk_bf16_f32 v70, v12, v13
	v_cvt_pk_bf16_f32 v71, v14, v15
	v_cvt_pk_bf16_f32 v72, v10, v11
	v_cvt_pk_bf16_f32 v73, v16, v17
	global_store_dwordx4 v82, v[70:73], s[10:11] sc1
	s_waitcnt vmcnt(8)
	v_max3_f32 v0, v88, v90, v92
	v_sub_f32_e32 v18, v88, v0
	v_sub_f32_e32 v36, v90, v0
	v_sub_f32_e32 v0, v92, v0
	v_cmp_gt_f32_e32 vcc, s19, v18
	v_cmp_gt_f32_e64 s[4:5], s19, v36
	v_cmp_gt_f32_e64 s[32:33], s19, v0
	v_cndmask_b32_e32 v37, 0, v4, vcc
	v_cndmask_b32_e64 v38, 0, v4, s[4:5]
	v_cndmask_b32_e64 v39, 0, v4, s[32:33]
	v_add_f32_e32 v18, v18, v37
	v_add_f32_e32 v36, v36, v38
	v_add_f32_e32 v0, v0, v39
	v_exp_f32_e32 v18, v18
	v_exp_f32_e32 v36, v36
	v_exp_f32_e32 v0, v0
	v_cndmask_b32_e32 v37, 0, v5, vcc
	v_cndmask_b32_e64 v38, 0, v5, s[4:5]
	v_cndmask_b32_e64 v39, 0, v5, s[32:33]
	v_mov_b32_e32 v20, v93
	v_mov_b32_e32 v21, v91
	v_ldexp_f32 v18, v18, v37
	v_ldexp_f32 v37, v36, v38
	v_ldexp_f32 v36, v0, v39
	v_mul_f32_e32 v0, v89, v18
	v_fma_f32 v38, v89, v18, 0
	v_pk_mul_f32 v[18:19], v[20:21], v[36:37]
	v_add_f32_e32 v20, v19, v38
	v_add_f32_e32 v20, v18, v20
	v_div_scale_f32 v21, s[4:5], v20, v20, 1.0
	v_rcp_f32_e32 v37, v21
	v_div_scale_f32 v36, vcc, 1.0, v20, 1.0
	v_fma_f32 v38, -v21, v37, 1.0
	v_fmac_f32_e32 v37, v38, v37
	v_mul_f32_e32 v38, v36, v37
	v_fma_f32 v39, -v21, v38, v36
	v_fmac_f32_e32 v38, v39, v37
	v_fma_f32 v21, -v21, v38, v36
	v_div_fmas_f32 v21, v21, v37, v38
	v_div_fixup_f32 v21, v21, v20, 1.0
	v_mul_f32_e32 v0, v0, v21
	v_mul_f32_e32 v20, v19, v21
	v_mul_f32_e32 v18, v18, v21
	v_lshlrev_b32_e32 v22, 16, v94
	v_and_b32_e32 v23, 0xffff0000, v94
	v_lshlrev_b32_e32 v6, 16, v95
	v_and_b32_e32 v7, 0xffff0000, v95
	v_lshlrev_b32_e32 v30, 16, v96
	v_and_b32_e32 v31, 0xffff0000, v96
	v_lshlrev_b32_e32 v8, 16, v97
	v_and_b32_e32 v9, 0xffff0000, v97
	v_lshlrev_b32_e32 v26, 16, v98
	v_and_b32_e32 v27, 0xffff0000, v98
	v_lshlrev_b32_e32 v10, 16, v99
	v_and_b32_e32 v11, 0xffff0000, v99
	v_lshlrev_b32_e32 v32, 16, v100
	v_and_b32_e32 v33, 0xffff0000, v100
	v_lshlrev_b32_e32 v12, 16, v101
	v_and_b32_e32 v13, 0xffff0000, v101
	v_pk_fma_f32 v[22:23], v[0:1], v[22:23], 0 op_sel_hi:[0,1,0]
	v_pk_fma_f32 v[6:7], v[0:1], v[6:7], 0 op_sel_hi:[0,1,0]
	v_pk_fma_f32 v[30:31], v[0:1], v[30:31], 0 op_sel_hi:[0,1,0]
	v_pk_fma_f32 v[8:9], v[0:1], v[8:9], 0 op_sel_hi:[0,1,0]
	v_lshlrev_b32_e32 v28, 16, v102
	v_and_b32_e32 v29, 0xffff0000, v102
	v_lshlrev_b32_e32 v14, 16, v103
	v_and_b32_e32 v15, 0xffff0000, v103
	v_lshlrev_b32_e32 v34, 16, v104
	v_and_b32_e32 v35, 0xffff0000, v104
	v_lshlrev_b32_e32 v16, 16, v105
	v_and_b32_e32 v17, 0xffff0000, v105
	v_pk_fma_f32 v[22:23], v[20:21], v[26:27], v[22:23] op_sel_hi:[0,1,1]
	v_pk_fma_f32 v[6:7], v[20:21], v[10:11], v[6:7] op_sel_hi:[0,1,1]
	v_pk_fma_f32 v[10:11], v[20:21], v[32:33], v[30:31] op_sel_hi:[0,1,1]
	v_pk_fma_f32 v[8:9], v[20:21], v[12:13], v[8:9] op_sel_hi:[0,1,1]
	v_pk_fma_f32 v[12:13], v[18:19], v[28:29], v[22:23] op_sel_hi:[0,1,1]
	v_pk_fma_f32 v[14:15], v[18:19], v[14:15], v[6:7] op_sel_hi:[0,1,1]
	v_pk_fma_f32 v[10:11], v[18:19], v[34:35], v[10:11] op_sel_hi:[0,1,1]
	v_pk_fma_f32 v[16:17], v[18:19], v[16:17], v[8:9] op_sel_hi:[0,1,1]
	v_cvt_pk_bf16_f32 v94, v12, v13
	v_cvt_pk_bf16_f32 v95, v14, v15
	v_cvt_pk_bf16_f32 v96, v10, v11
	v_cvt_pk_bf16_f32 v97, v16, v17
	global_store_dwordx4 v106, v[94:97], s[10:11] sc1
	s_waitcnt vmcnt(3)
; __device__ __forceinline__ unsigned pk2(float lo, float hi) { f32x2_t v = {lo, hi}; bf16x2_t b = __builtin_convertvector(v, bf16x2_t); return __builtin_bit_cast(unsigned, b); }
; __device__ __forceinline__ float bflo(unsigned w) { return __uint_as_float(w << 16); }
; __device__ __forceinline__ float bfhi(unsigned w) { return __uint_as_float(w & 0xffff0000u); }
; __device__ __forceinline__ bf16* po_base(unsigned char* ws, int pat) { return (bf16*)(ws + (pat < 2 ? 436 * MiB + (size_t)pat * 32 * MiB : WS_Y)); }
; __device__ __forceinline__ void attn_combine(unsigned char* ws, const float* __restrict__ PM, bf16* CAT, int gtid, int gthreads, int iend = S * 128) {
;     for (int idx = gtid; idx < iend; idx += gthreads) {
;         const int t = idx >> 7, c = (idx & 127) * 8, hh = c >> 7;
;         float mm[3], ll[3];
; #pragma unroll
;         for (int p = 0; p < 3; ++p) { const f32x2_t ml = *(const f32x2_t*)(PM + (((size_t)p * S + t) * 8 + hh) * 2); mm[p] = ml[0]; ll[p] = ml[1]; }
;         const float ma = fmaxf(mm[0], fmaxf(mm[1], mm[2]));
;         float w[3], den = 0.f;
; #pragma unroll
;         for (int p = 0; p < 3; ++p) { w[p] = exp2f(mm[p] - ma) * ll[p]; den += w[p]; }
;         const float inv = 1.f / den;
;         float o[8] = {0.f, 0.f, 0.f, 0.f, 0.f, 0.f, 0.f, 0.f};
; #pragma unroll
;         for (int p = 0; p < 3; ++p) {
;             const u32x4 v = *(const u32x4*)(po_base(ws, p) + (size_t)t * 1024 + c); const float wp = w[p] * inv;
;             o[0] += wp * bflo(v.x); o[1] += wp * bfhi(v.x); o[2] += wp * bflo(v.y); o[3] += wp * bfhi(v.y); o[4] += wp * bflo(v.z); o[5] += wp * bfhi(v.z); o[6] += wp * bflo(v.w); o[7] += wp * bfhi(v.w);
;         }
;         u32x4 ov; ov.x = pk2(o[0], o[1]); ov.y = pk2(o[2], o[3]); ov.z = pk2(o[4], o[5]); ov.w = pk2(o[6], o[7]);
;         *(u32x4*)(CAT + (size_t)t * 2048 + c) = ov;
	v_max3_f32 v0, v112, v114, v116
	v_sub_f32_e32 v18, v112, v0
	v_sub_f32_e32 v36, v114, v0
	v_sub_f32_e32 v0, v116, v0
	v_cmp_gt_f32_e32 vcc, s19, v18
	v_cmp_gt_f32_e64 s[4:5], s19, v36
	v_cmp_gt_f32_e64 s[32:33], s19, v0
	v_cndmask_b32_e32 v37, 0, v4, vcc
	v_cndmask_b32_e64 v38, 0, v4, s[4:5]
	v_cndmask_b32_e64 v39, 0, v4, s[32:33]
	v_add_f32_e32 v18, v18, v37
	v_add_f32_e32 v36, v36, v38
	v_add_f32_e32 v0, v0, v39
	v_exp_f32_e32 v18, v18
	v_exp_f32_e32 v36, v36
	v_exp_f32_e32 v0, v0
	v_cndmask_b32_e32 v37, 0, v5, vcc
	v_cndmask_b32_e64 v38, 0, v5, s[4:5]
	v_cndmask_b32_e64 v39, 0, v5, s[32:33]
	v_mov_b32_e32 v20, v117
	v_mov_b32_e32 v21, v115
	v_ldexp_f32 v18, v18, v37
	v_ldexp_f32 v37, v36, v38
	v_ldexp_f32 v36, v0, v39
	v_mul_f32_e32 v0, v113, v18
	v_fma_f32 v38, v113, v18, 0
	v_pk_mul_f32 v[18:19], v[20:21], v[36:37]
	v_add_f32_e32 v20, v19, v38
	v_add_f32_e32 v20, v18, v20
	v_div_scale_f32 v21, s[4:5], v20, v20, 1.0
	v_rcp_f32_e32 v37, v21
	v_div_scale_f32 v36, vcc, 1.0, v20, 1.0
	v_fma_f32 v38, -v21, v37, 1.0
	v_fmac_f32_e32 v37, v38, v37
	v_mul_f32_e32 v38, v36, v37
	v_fma_f32 v39, -v21, v38, v36
	v_fmac_f32_e32 v38, v39, v37
	v_fma_f32 v21, -v21, v38, v36
	v_div_fmas_f32 v21, v21, v37, v38
	v_div_fixup_f32 v21, v21, v20, 1.0
	v_mul_f32_e32 v0, v0, v21
	v_mul_f32_e32 v20, v19, v21
	v_mul_f32_e32 v18, v18, v21
	v_lshlrev_b32_e32 v22, 16, v118
	v_and_b32_e32 v23, 0xffff0000, v118
	v_lshlrev_b32_e32 v6, 16, v119
	v_and_b32_e32 v7, 0xffff0000, v119
	v_lshlrev_b32_e32 v30, 16, v120
	v_and_b32_e32 v31, 0xffff0000, v120
	v_lshlrev_b32_e32 v8, 16, v121
	v_and_b32_e32 v9, 0xffff0000, v121
	v_lshlrev_b32_e32 v26, 16, v122
	v_and_b32_e32 v27, 0xffff0000, v122
	v_lshlrev_b32_e32 v10, 16, v123
	v_and_b32_e32 v11, 0xffff0000, v123
	v_lshlrev_b32_e32 v32, 16, v124
	v_and_b32_e32 v33, 0xffff0000, v124
	v_lshlrev_b32_e32 v12, 16, v125
	v_and_b32_e32 v13, 0xffff0000, v125
	v_pk_fma_f32 v[22:23], v[0:1], v[22:23], 0 op_sel_hi:[0,1,0]
	v_pk_fma_f32 v[6:7], v[0:1], v[6:7], 0 op_sel_hi:[0,1,0]
	v_pk_fma_f32 v[30:31], v[0:1], v[30:31], 0 op_sel_hi:[0,1,0]
	v_pk_fma_f32 v[8:9], v[0:1], v[8:9], 0 op_sel_hi:[0,1,0]
	v_lshlrev_b32_e32 v28, 16, v126
	v_and_b32_e32 v29, 0xffff0000, v126
	v_lshlrev_b32_e32 v14, 16, v127
	v_and_b32_e32 v15, 0xffff0000, v127
	v_lshlrev_b32_e32 v34, 16, v128
	v_and_b32_e32 v35, 0xffff0000, v128
	v_lshlrev_b32_e32 v16, 16, v129
	v_and_b32_e32 v17, 0xffff0000, v129
	v_pk_fma_f32 v[22:23], v[20:21], v[26:27], v[22:23] op_sel_hi:[0,1,1]
	v_pk_fma_f32 v[6:7], v[20:21], v[10:11], v[6:7] op_sel_hi:[0,1,1]
	v_pk_fma_f32 v[10:11], v[20:21], v[32:33], v[30:31] op_sel_hi:[0,1,1]
	v_pk_fma_f32 v[8:9], v[20:21], v[12:13], v[8:9] op_sel_hi:[0,1,1]
	v_pk_fma_f32 v[12:13], v[18:19], v[28:29], v[22:23] op_sel_hi:[0,1,1]
	v_pk_fma_f32 v[14:15], v[18:19], v[14:15], v[6:7] op_sel_hi:[0,1,1]
	v_pk_fma_f32 v[10:11], v[18:19], v[34:35], v[10:11] op_sel_hi:[0,1,1]
	v_pk_fma_f32 v[16:17], v[18:19], v[16:17], v[8:9] op_sel_hi:[0,1,1]
	v_cvt_pk_bf16_f32 v118, v12, v13
	v_cvt_pk_bf16_f32 v119, v14, v15
	v_cvt_pk_bf16_f32 v120, v10, v11
	v_cvt_pk_bf16_f32 v121, v16, v17
	global_store_dwordx4 v130, v[118:121], s[10:11] sc1
	s_cmp_lg_u32 s0, 0
	s_cbranch_scc1 .Lcmb_loop
